# speedup vs baseline: 1.0037x; 1.0037x over previous
; DEV float bf2f(u16 b) { return __uint_as_float(((unsigned)b) << 16); }
; DEV u16 f2bf(float f) { return (u16)(cvt_pk_bf16(f, 0.f) & 0xffffu); }
; DEV float wsum(float v) { for (int o = 32; o > 0; o >>= 1) v += __shfl_xor(v, o); return v; }
; DEV void gmlp_unit(LAS unsigned char* lds, const P& p, int c, int g) {
;     ...
; #pragma unroll 4
;     for (int jr = 0; jr < 16; ++jr) { const int j = wid * 16 + jr; const u16* vr = UV + (size_t)(c * 128 + j) * 4096 + 2048 + g * 512;
;         float v[8]; float sm = 0.f;
; #pragma unroll
;         for (int e = 0; e < 8; ++e) { v[e] = bf2f(vr[lane + 64 * e]); sm += v[e]; }
;         const float mu = wsum(sm) * (1.0f / 512.0f); float sq = 0.f;
; #pragma unroll
;         for (int e = 0; e < 8; ++e) { v[e] -= mu; sq += v[e] * v[e]; }
;         const float rs = rsqrtf(wsum(sq) * (1.0f / 512.0f) + EPS);
; #pragma unroll
;         for (int e = 0; e < 8; ++e) VnT[(lane + 64 * e) * VS + j] = f2bf(v[e] * rs * lg[e] + lb[e]); }
.LBB0_519:
	v_lshl_add_u64 v[2:3], v[0:1], 0, s[0:1]
	v_add_co_u32_e32 v72, vcc, 0x1bf21000, v2
	s_nop 1
	v_addc_co_u32_e32 v73, vcc, 0, v3, vcc
	v_add_co_u32_e32 v74, vcc, 0x2000, v72
	s_nop 1
	v_addc_co_u32_e32 v75, vcc, 0, v73, vcc
	v_add_co_u32_e32 v76, vcc, 0x4000, v72
	s_nop 1
	v_addc_co_u32_e32 v77, vcc, 0, v73, vcc
	v_add_co_u32_e32 v78, vcc, 0x6000, v72
	s_nop 1
	v_addc_co_u32_e32 v79, vcc, 0, v73, vcc
	global_load_ushort v124, v[72:73], off
	global_load_ushort v125, v[72:73], off offset:128
	global_load_ushort v126, v[72:73], off offset:256
	global_load_ushort v127, v[72:73], off offset:384
	global_load_ushort v128, v[72:73], off offset:896
	global_load_ushort v129, v[72:73], off offset:768
	global_load_ushort v130, v[72:73], off offset:640
	global_load_ushort v131, v[72:73], off offset:512
	global_load_ushort v132, v[74:75], off
	global_load_ushort v133, v[74:75], off offset:128
	global_load_ushort v134, v[74:75], off offset:256
	global_load_ushort v135, v[74:75], off offset:384
	global_load_ushort v136, v[74:75], off offset:896
	global_load_ushort v137, v[74:75], off offset:768
	global_load_ushort v138, v[74:75], off offset:640
	global_load_ushort v139, v[74:75], off offset:512
	global_load_ushort v140, v[76:77], off
	global_load_ushort v141, v[76:77], off offset:128
	global_load_ushort v142, v[76:77], off offset:256
	global_load_ushort v143, v[76:77], off offset:384
	global_load_ushort v144, v[76:77], off offset:896
	global_load_ushort v145, v[76:77], off offset:768
	global_load_ushort v146, v[76:77], off offset:640
	global_load_ushort v147, v[76:77], off offset:512
	global_load_ushort v148, v[78:79], off
	global_load_ushort v149, v[78:79], off offset:128
	global_load_ushort v150, v[78:79], off offset:256
	global_load_ushort v151, v[78:79], off offset:384
	global_load_ushort v152, v[78:79], off offset:896
	global_load_ushort v153, v[78:79], off offset:768
	global_load_ushort v154, v[78:79], off offset:640
	global_load_ushort v155, v[78:79], off offset:512
	v_add_co_u32_e32 v4, vcc, 0x1bf21000, v2
	s_mov_b32 s11, 0x1bf23000
	s_nop 0
	v_addc_co_u32_e32 v5, vcc, 0, v3, vcc
	v_add_u32_e32 v47, 0x4100, v32
	v_add_u32_e32 v49, 0x8200, v32
	s_add_u32 s0, s0, 0x8000
	s_addc_u32 s1, s1, 0
	v_add_u32_e32 v46, 0xffffbf00, v32
	v_add_u32_e32 v51, 0xc300, v32
	s_cmp_eq_u32 s0, 0x20000
	s_waitcnt vmcnt(0)
	v_lshlrev_b32_e32 v33, 16, v124
	v_lshlrev_b32_e32 v37, 16, v125
	v_add_f32_e32 v6, 0, v33
	v_add_f32_e32 v6, v6, v37
	s_waitcnt vmcnt(0)
	v_lshlrev_b32_e32 v38, 16, v126
	v_add_f32_e32 v6, v6, v38
	s_waitcnt vmcnt(0)
	v_lshlrev_b32_e32 v40, 16, v127
	v_add_f32_e32 v6, v6, v40
	s_waitcnt vmcnt(0)
	v_lshlrev_b32_e32 v35, 16, v129
	v_lshlrev_b32_e32 v34, 16, v128
	s_nop 0
	s_waitcnt vmcnt(0)
	v_lshlrev_b32_e32 v5, 16, v131
	v_lshlrev_b32_e32 v4, 16, v130
	v_add_f32_e32 v6, v6, v5
	v_add_f32_e32 v6, v6, v4
	v_add_f32_e32 v6, v6, v35
	v_add_f32_e32 v6, v6, v34
	ds_bpermute_b32 v7, v26, v6
	s_waitcnt lgkmcnt(0)
	v_add_f32_e32 v6, v6, v7
	ds_bpermute_b32 v7, v27, v6
	s_waitcnt lgkmcnt(0)
	v_add_f32_e32 v6, v6, v7
	ds_bpermute_b32 v7, v28, v6
	s_waitcnt lgkmcnt(0)
	v_add_f32_e32 v6, v6, v7
	ds_bpermute_b32 v7, v29, v6
	s_waitcnt lgkmcnt(0)
	v_add_f32_e32 v6, v6, v7
	ds_bpermute_b32 v7, v30, v6
	s_waitcnt lgkmcnt(0)
	v_add_f32_e32 v6, v6, v7
	ds_bpermute_b32 v7, v31, v6
	s_waitcnt lgkmcnt(0)
	v_add_f32_e32 v6, v6, v7
	v_fmac_f32_e32 v37, 0xbb000000, v6
	v_fmac_f32_e32 v33, 0xbb000000, v6
	v_mul_f32_e32 v39, v37, v37
	v_mul_f32_e32 v36, 0x3b000000, v6
	v_fmac_f32_e32 v39, v33, v33
	v_fmac_f32_e32 v38, 0xbb000000, v6
	v_fmac_f32_e32 v39, v38, v38
	v_fmac_f32_e32 v40, 0xbb000000, v6
	v_pk_add_f32 v[6:7], v[4:5], v[36:37] op_sel_hi:[1,0] neg_lo:[0,1] neg_hi:[0,1]
	v_fmac_f32_e32 v39, v40, v40
	v_pk_mul_f32 v[4:5], v[6:7], v[6:7]
	s_nop 0
	v_add_f32_e32 v5, v5, v39
	v_add_f32_e32 v39, v4, v5
	v_pk_add_f32 v[4:5], v[34:35], v[36:37] op_sel_hi:[1,0] neg_lo:[0,1] neg_hi:[0,1]
	s_nop 0
	v_pk_mul_f32 v[34:35], v[4:5], v[4:5]
	s_nop 0
	v_add_f32_e32 v35, v35, v39
	v_add_f32_e32 v34, v34, v35
	ds_bpermute_b32 v35, v26, v34
	v_add_u32_e32 v39, 0xffff7e00, v32
	s_waitcnt lgkmcnt(0)
	v_add_f32_e32 v34, v34, v35
	ds_bpermute_b32 v35, v27, v34
	s_waitcnt lgkmcnt(0)
	v_add_f32_e32 v34, v34, v35
	ds_bpermute_b32 v35, v28, v34
	s_waitcnt lgkmcnt(0)
	v_add_f32_e32 v34, v34, v35
	ds_bpermute_b32 v35, v29, v34
	s_waitcnt lgkmcnt(0)
	v_add_f32_e32 v34, v34, v35
	ds_bpermute_b32 v35, v30, v34
	s_waitcnt lgkmcnt(0)
	v_add_f32_e32 v34, v34, v35
	ds_bpermute_b32 v35, v31, v34
	s_waitcnt lgkmcnt(0)
	v_add_f32_e32 v34, v34, v35
	v_fmamk_f32 v34, v34, 0x3b000000, v199
	v_cmp_gt_f32_e32 vcc, s12, v34
	v_mul_f32_e32 v35, 0x4b800000, v34
	s_nop 0
	v_cndmask_b32_e32 v34, v34, v35, vcc
	v_rsq_f32_e32 v34, v34
	s_nop 0
	v_mul_f32_e32 v35, 0x45800000, v34
	v_cndmask_b32_e32 v41, v34, v35, vcc
	v_mul_f32_e32 v4, v4, v41
	v_mul_f32_e32 v5, v5, v41
	v_fma_f32 v50, v24, v4, v25
	v_add_co_u32_e32 v4, vcc, s11, v2
	v_fma_f32 v48, v22, v5, v23
	s_nop 0
	v_addc_co_u32_e32 v5, vcc, 0, v3, vcc
	v_mul_f32_e32 v33, v33, v41
	v_mul_f32_e32 v34, v37, v41
	v_mul_f32_e32 v36, v38, v41
	v_mul_f32_e32 v38, v40, v41
	v_mul_f32_e32 v7, v7, v41
	v_mul_f32_e32 v6, v6, v41
	s_mov_b32 s11, 0x1bf25000
	v_fma_f32 v33, v10, v33, v11
	v_add_u32_e32 v35, 0xfffefc00, v32
	v_fma_f32 v7, v18, v7, v19
	v_fma_f32 v34, v12, v34, v13
	v_fma_f32 v6, v20, v6, v21
	v_add_u32_e32 v37, 0xffff3d00, v32
	v_fma_f32 v36, v14, v36, v15
	v_fma_f32 v38, v16, v38, v17
	s_waitcnt vmcnt(1)
	v_lshlrev_b32_e32 v52, 16, v132
	s_waitcnt vmcnt(0)
	v_lshlrev_b32_e32 v53, 16, v133
	v_add_f32_e32 v40, 0, v52
	v_add_f32_e32 v40, v40, v53
	s_waitcnt vmcnt(0)
; DEV float bf2f(u16 b) { return __uint_as_float(((unsigned)b) << 16); }
; DEV u16 f2bf(float f) { return (u16)(cvt_pk_bf16(f, 0.f) & 0xffffu); }
; DEV float wsum(float v) { for (int o = 32; o > 0; o >>= 1) v += __shfl_xor(v, o); return v; }
; DEV void gmlp_unit(LAS unsigned char* lds, const P& p, int c, int g) {
;     ...
;         float v[8]; float sm = 0.f;
; #pragma unroll
;         for (int e = 0; e < 8; ++e) { v[e] = bf2f(vr[lane + 64 * e]); sm += v[e]; }
;         const float mu = wsum(sm) * (1.0f / 512.0f); float sq = 0.f;
; #pragma unroll
;         for (int e = 0; e < 8; ++e) { v[e] -= mu; sq += v[e] * v[e]; }
;         const float rs = rsqrtf(wsum(sq) * (1.0f / 512.0f) + EPS);
; #pragma unroll
;         for (int e = 0; e < 8; ++e) VnT[(lane + 64 * e) * VS + j] = f2bf(v[e] * rs * lg[e] + lb[e]); }
	v_lshlrev_b32_e32 v54, 16, v134
	v_add_f32_e32 v40, v40, v54
	s_waitcnt vmcnt(0)
	v_lshlrev_b32_e32 v55, 16, v135
	v_add_f32_e32 v42, v40, v55
	s_nop 0
	s_waitcnt vmcnt(3)
	v_lshlrev_b32_e32 v40, 16, v136
	s_waitcnt vmcnt(2)
	v_lshlrev_b32_e32 v41, 16, v137
	s_waitcnt vmcnt(0)
	v_lshlrev_b32_e32 v5, 16, v139
	v_lshlrev_b32_e32 v4, 16, v138
	v_add_f32_e32 v42, v42, v5
	v_add_f32_e32 v42, v42, v4
	v_add_f32_e32 v42, v42, v41
	v_add_f32_e32 v42, v42, v40
	ds_bpermute_b32 v43, v26, v42
	s_waitcnt lgkmcnt(0)
	v_add_f32_e32 v42, v42, v43
	ds_bpermute_b32 v43, v27, v42
	s_waitcnt lgkmcnt(0)
	v_add_f32_e32 v42, v42, v43
	ds_bpermute_b32 v43, v28, v42
	s_waitcnt lgkmcnt(0)
	v_add_f32_e32 v42, v42, v43
	ds_bpermute_b32 v43, v29, v42
	s_waitcnt lgkmcnt(0)
	v_add_f32_e32 v42, v42, v43
	ds_bpermute_b32 v43, v30, v42
	s_waitcnt lgkmcnt(0)
	v_add_f32_e32 v42, v42, v43
	ds_bpermute_b32 v43, v31, v42
	s_waitcnt lgkmcnt(0)
	v_add_f32_e32 v43, v42, v43
	v_fmac_f32_e32 v53, 0xbb000000, v43
	v_fmac_f32_e32 v52, 0xbb000000, v43
	v_mul_f32_e32 v56, v53, v53
	v_mul_f32_e32 v42, 0x3b000000, v43
	v_fmac_f32_e32 v56, v52, v52
	v_fmac_f32_e32 v54, 0xbb000000, v43
	v_fmac_f32_e32 v56, v54, v54
	v_fmac_f32_e32 v55, 0xbb000000, v43
	v_pk_add_f32 v[4:5], v[4:5], v[42:43] op_sel_hi:[1,0] neg_lo:[0,1] neg_hi:[0,1]
	v_fmac_f32_e32 v56, v55, v55
	v_pk_mul_f32 v[44:45], v[4:5], v[4:5]
	s_nop 0
	v_add_f32_e32 v43, v45, v56
	v_pk_add_f32 v[40:41], v[40:41], v[42:43] op_sel_hi:[1,0] neg_lo:[0,1] neg_hi:[0,1]
	v_add_f32_e32 v44, v44, v43
	v_pk_mul_f32 v[42:43], v[40:41], v[40:41]
	s_nop 0
	v_add_f32_e32 v43, v43, v44
	v_add_f32_e32 v42, v42, v43
	ds_bpermute_b32 v43, v26, v42
	s_waitcnt lgkmcnt(0)
	v_add_f32_e32 v42, v42, v43
	ds_bpermute_b32 v43, v27, v42
	s_waitcnt lgkmcnt(0)
	v_add_f32_e32 v42, v42, v43
	ds_bpermute_b32 v43, v28, v42
	s_waitcnt lgkmcnt(0)
	v_add_f32_e32 v42, v42, v43
	ds_bpermute_b32 v43, v29, v42
	s_waitcnt lgkmcnt(0)
	v_add_f32_e32 v42, v42, v43
	ds_bpermute_b32 v43, v30, v42
	s_waitcnt lgkmcnt(0)
	v_add_f32_e32 v42, v42, v43
	ds_bpermute_b32 v43, v31, v42
	s_waitcnt lgkmcnt(0)
	v_add_f32_e32 v42, v42, v43
	v_fmamk_f32 v42, v42, 0x3b000000, v199
	v_cmp_gt_f32_e32 vcc, s12, v42
	v_mul_f32_e32 v43, 0x4b800000, v42
	s_nop 0
	v_cndmask_b32_e32 v42, v42, v43, vcc
	v_rsq_f32_e32 v42, v42
	s_nop 0
	v_mul_f32_e32 v43, 0x45800000, v42
	v_cndmask_b32_e32 v42, v42, v43, vcc
	v_mul_f32_e32 v4, v4, v42
	v_fma_f32 v57, v20, v4, v21
	v_mul_f32_e32 v4, v41, v42
	v_fma_f32 v58, v22, v4, v23
	v_mul_f32_e32 v4, v40, v42
	v_mul_f32_e32 v5, v5, v42
	v_fma_f32 v59, v24, v4, v25
	v_add_co_u32_e32 v4, vcc, s11, v2
	v_fma_f32 v56, v18, v5, v19
	s_nop 0
	v_addc_co_u32_e32 v5, vcc, 0, v3, vcc
	v_mul_f32_e32 v43, v52, v42
	v_fma_f32 v52, v10, v43, v11
	v_mul_f32_e32 v43, v53, v42
	v_fma_f32 v53, v12, v43, v13
	v_mul_f32_e32 v43, v54, v42
	v_fma_f32 v54, v14, v43, v15
	v_mul_f32_e32 v43, v55, v42
	v_fma_f32 v55, v16, v43, v17
	s_mov_b32 s11, 0x1bf27000
	v_cvt_pk_bf16_f32 v33, v33, v52
	v_cvt_pk_bf16_f32 v7, v7, v56
	v_cvt_pk_bf16_f32 v34, v34, v53
	s_waitcnt vmcnt(1)
	v_lshlrev_b32_e32 v60, 16, v140
	s_waitcnt vmcnt(0)
	v_lshlrev_b32_e32 v61, 16, v141
	v_add_f32_e32 v40, 0, v60
	v_add_f32_e32 v40, v40, v61
	s_waitcnt vmcnt(0)
	v_lshlrev_b32_e32 v62, 16, v142
	v_add_f32_e32 v40, v40, v62
	s_waitcnt vmcnt(0)
	v_lshlrev_b32_e32 v63, 16, v143
	v_add_f32_e32 v42, v40, v63
	s_nop 0
	s_waitcnt vmcnt(3)
	v_lshlrev_b32_e32 v40, 16, v144
	s_waitcnt vmcnt(2)
	v_lshlrev_b32_e32 v41, 16, v145
	s_waitcnt vmcnt(0)
	v_lshlrev_b32_e32 v5, 16, v147
	v_lshlrev_b32_e32 v4, 16, v146
	v_add_f32_e32 v42, v42, v5
	v_add_f32_e32 v42, v42, v4
	v_add_f32_e32 v42, v42, v41
	v_add_f32_e32 v42, v42, v40
	ds_bpermute_b32 v43, v26, v42
	s_waitcnt lgkmcnt(0)
	v_add_f32_e32 v42, v42, v43
	ds_bpermute_b32 v43, v27, v42
	s_waitcnt lgkmcnt(0)
	v_add_f32_e32 v42, v42, v43
	ds_bpermute_b32 v43, v28, v42
	s_waitcnt lgkmcnt(0)
	v_add_f32_e32 v42, v42, v43
	ds_bpermute_b32 v43, v29, v42
	s_waitcnt lgkmcnt(0)
	v_add_f32_e32 v42, v42, v43
	ds_bpermute_b32 v43, v30, v42
	s_waitcnt lgkmcnt(0)
	v_add_f32_e32 v42, v42, v43
	ds_bpermute_b32 v43, v31, v42
	s_waitcnt lgkmcnt(0)
	v_add_f32_e32 v43, v42, v43
	v_fmac_f32_e32 v61, 0xbb000000, v43
	v_fmac_f32_e32 v60, 0xbb000000, v43
	v_mul_f32_e32 v64, v61, v61
	v_mul_f32_e32 v42, 0x3b000000, v43
	v_fmac_f32_e32 v64, v60, v60
	v_fmac_f32_e32 v62, 0xbb000000, v43
	v_fmac_f32_e32 v64, v62, v62
	v_fmac_f32_e32 v63, 0xbb000000, v43
	v_pk_add_f32 v[4:5], v[4:5], v[42:43] op_sel_hi:[1,0] neg_lo:[0,1] neg_hi:[0,1]
	v_fmac_f32_e32 v64, v63, v63
	v_pk_mul_f32 v[44:45], v[4:5], v[4:5]
	s_nop 0
	v_add_f32_e32 v43, v45, v64
	v_pk_add_f32 v[40:41], v[40:41], v[42:43] op_sel_hi:[1,0] neg_lo:[0,1] neg_hi:[0,1]
	v_add_f32_e32 v44, v44, v43
	v_pk_mul_f32 v[42:43], v[40:41], v[40:41]
	s_nop 0
	v_add_f32_e32 v43, v43, v44
	v_add_f32_e32 v42, v42, v43
	ds_bpermute_b32 v43, v26, v42
	s_waitcnt lgkmcnt(0)
	v_add_f32_e32 v42, v42, v43
	ds_bpermute_b32 v43, v27, v42
	s_waitcnt lgkmcnt(0)
	v_add_f32_e32 v42, v42, v43
	ds_bpermute_b32 v43, v28, v42
	s_waitcnt lgkmcnt(0)
	v_add_f32_e32 v42, v42, v43
	ds_bpermute_b32 v43, v29, v42
	s_waitcnt lgkmcnt(0)
	v_add_f32_e32 v42, v42, v43
	ds_bpermute_b32 v43, v30, v42
	s_waitcnt lgkmcnt(0)
	v_add_f32_e32 v42, v42, v43
	ds_bpermute_b32 v43, v31, v42
	s_waitcnt lgkmcnt(0)
; #define LAS __attribute__((address_space(3)))
; DEV float bf2f(u16 b) { return __uint_as_float(((unsigned)b) << 16); }
; DEV u16 f2bf(float f) { return (u16)(cvt_pk_bf16(f, 0.f) & 0xffffu); }
; DEV float wsum(float v) { for (int o = 32; o > 0; o >>= 1) v += __shfl_xor(v, o); return v; }
; DEV void gmlp_unit(LAS unsigned char* lds, const P& p, int c, int g) {
;     ...
; #pragma unroll 4
;     for (int jr = 0; jr < 16; ++jr) { const int j = wid * 16 + jr; const u16* vr = UV + (size_t)(c * 128 + j) * 4096 + 2048 + g * 512;
;         float v[8]; float sm = 0.f;
; #pragma unroll
;         for (int e = 0; e < 8; ++e) { v[e] = bf2f(vr[lane + 64 * e]); sm += v[e]; }
;         const float mu = wsum(sm) * (1.0f / 512.0f); float sq = 0.f;
; #pragma unroll
;         for (int e = 0; e < 8; ++e) { v[e] -= mu; sq += v[e] * v[e]; }
;         const float rs = rsqrtf(wsum(sq) * (1.0f / 512.0f) + EPS);
; #pragma unroll
;         for (int e = 0; e < 8; ++e) VnT[(lane + 64 * e) * VS + j] = f2bf(v[e] * rs * lg[e] + lb[e]); }
;     __syncthreads();
;     ...
;         const int nks = half ? 4 : 2;
; #pragma unroll 1
;         for (int ks = 0; ks < nks; ++ks) {
;             bf16x8 bt[4], af[4];
; #pragma unroll
;             for (int nt = 0; nt < 4; ++nt) { const LAS unsigned* bp = (const LAS unsigned*)(VnT + (wid * 64 + nt * 16 + fr) * VS + ks * 32 + fq * 8);
;                 u32x4 w; w.x = bp[0]; w.y = bp[1]; w.z = bp[2]; w.w = bp[3]; bt[nt] = __builtin_bit_cast(bf16x8, w); }
; #pragma unroll
;             for (int mt = 0; mt < 4; ++mt) af[mt] = *(const bf16x8*)(TRIL + (size_t)(g * 128 + (half * 4 + mt) * 16 + fr) * 128 + ks * 32 + fq * 8);
	v_add_f32_e32 v42, v42, v43
	v_fmamk_f32 v42, v42, 0x3b000000, v199
	v_cmp_gt_f32_e32 vcc, s12, v42
	v_mul_f32_e32 v43, 0x4b800000, v42
	s_nop 0
	v_cndmask_b32_e32 v42, v42, v43, vcc
	v_rsq_f32_e32 v42, v42
	s_nop 0
	v_mul_f32_e32 v43, 0x45800000, v42
	v_cndmask_b32_e32 v42, v42, v43, vcc
	v_mul_f32_e32 v43, v60, v42
	v_fma_f32 v44, v10, v43, v11
	v_mul_f32_e32 v43, v61, v42
	v_fma_f32 v45, v12, v43, v13
	v_mul_f32_e32 v43, v62, v42
	v_mul_f32_e32 v4, v4, v42
	v_fma_f32 v60, v14, v43, v15
	v_mul_f32_e32 v43, v63, v42
	v_fma_f32 v63, v20, v4, v21
	v_mul_f32_e32 v4, v41, v42
	v_add_co_u32_e32 v2, vcc, s11, v2
	v_mul_f32_e32 v5, v5, v42
	v_fma_f32 v64, v22, v4, v23
	v_mul_f32_e32 v4, v40, v42
	v_addc_co_u32_e32 v3, vcc, 0, v3, vcc
	v_fma_f32 v62, v18, v5, v19
	v_fma_f32 v65, v24, v4, v25
	v_fma_f32 v61, v16, v43, v17
	s_waitcnt vmcnt(1)
	v_lshlrev_b32_e32 v66, 16, v148
	s_waitcnt vmcnt(0)
	v_lshlrev_b32_e32 v67, 16, v149
	v_add_f32_e32 v4, 0, v66
	v_add_f32_e32 v4, v4, v67
	s_waitcnt vmcnt(0)
	v_lshlrev_b32_e32 v68, 16, v150
	v_add_f32_e32 v4, v4, v68
	s_waitcnt vmcnt(0)
	v_lshlrev_b32_e32 v69, 16, v151
	v_add_f32_e32 v40, v4, v69
	s_nop 0
	s_waitcnt vmcnt(3)
	v_lshlrev_b32_e32 v4, 16, v152
	s_waitcnt vmcnt(2)
	v_lshlrev_b32_e32 v5, 16, v153
	s_waitcnt vmcnt(0)
	v_lshlrev_b32_e32 v3, 16, v155
	v_lshlrev_b32_e32 v2, 16, v154
	v_add_f32_e32 v40, v40, v3
	v_add_f32_e32 v40, v40, v2
	v_add_f32_e32 v40, v40, v5
	v_add_f32_e32 v40, v40, v4
	ds_bpermute_b32 v41, v26, v40
	s_waitcnt lgkmcnt(0)
	v_add_f32_e32 v40, v40, v41
	ds_bpermute_b32 v41, v27, v40
	s_waitcnt lgkmcnt(0)
	v_add_f32_e32 v40, v40, v41
	ds_bpermute_b32 v41, v28, v40
	s_waitcnt lgkmcnt(0)
	v_add_f32_e32 v40, v40, v41
	ds_bpermute_b32 v41, v29, v40
	s_waitcnt lgkmcnt(0)
	v_add_f32_e32 v40, v40, v41
	ds_bpermute_b32 v41, v30, v40
	s_waitcnt lgkmcnt(0)
	v_add_f32_e32 v40, v40, v41
	ds_bpermute_b32 v41, v31, v40
	s_waitcnt lgkmcnt(0)
	v_add_f32_e32 v41, v40, v41
	v_fmac_f32_e32 v67, 0xbb000000, v41
	v_fmac_f32_e32 v66, 0xbb000000, v41
	v_mul_f32_e32 v70, v67, v67
	v_mul_f32_e32 v40, 0x3b000000, v41
	v_fmac_f32_e32 v70, v66, v66
	v_fmac_f32_e32 v68, 0xbb000000, v41
	v_fmac_f32_e32 v70, v68, v68
	v_fmac_f32_e32 v69, 0xbb000000, v41
	v_pk_add_f32 v[2:3], v[2:3], v[40:41] op_sel_hi:[1,0] neg_lo:[0,1] neg_hi:[0,1]
	v_fmac_f32_e32 v70, v69, v69
	v_pk_mul_f32 v[42:43], v[2:3], v[2:3]
	s_nop 0
	v_add_f32_e32 v41, v43, v70
	v_pk_add_f32 v[4:5], v[4:5], v[40:41] op_sel_hi:[1,0] neg_lo:[0,1] neg_hi:[0,1]
	v_add_f32_e32 v42, v42, v41
	v_pk_mul_f32 v[40:41], v[4:5], v[4:5]
	s_nop 0
	v_add_f32_e32 v41, v41, v42
	v_add_f32_e32 v40, v40, v41
	ds_bpermute_b32 v41, v26, v40
	s_waitcnt lgkmcnt(0)
	v_add_f32_e32 v40, v40, v41
	ds_bpermute_b32 v41, v27, v40
	s_waitcnt lgkmcnt(0)
	v_add_f32_e32 v40, v40, v41
	ds_bpermute_b32 v41, v28, v40
	s_waitcnt lgkmcnt(0)
	v_add_f32_e32 v40, v40, v41
	ds_bpermute_b32 v41, v29, v40
	s_waitcnt lgkmcnt(0)
	v_add_f32_e32 v40, v40, v41
	ds_bpermute_b32 v41, v30, v40
	s_waitcnt lgkmcnt(0)
	v_add_f32_e32 v40, v40, v41
	ds_bpermute_b32 v41, v31, v40
	s_waitcnt lgkmcnt(0)
	v_add_f32_e32 v40, v40, v41
	v_fmamk_f32 v40, v40, 0x3b000000, v199
	v_cmp_gt_f32_e32 vcc, s12, v40
	v_mul_f32_e32 v41, 0x4b800000, v40
	s_nop 0
	v_cndmask_b32_e32 v40, v40, v41, vcc
	v_rsq_f32_e32 v40, v40
	s_nop 0
	v_mul_f32_e32 v41, 0x45800000, v40
	v_cndmask_b32_e32 v40, v40, v41, vcc
	v_mul_f32_e32 v41, v66, v40
	v_fma_f32 v41, v10, v41, v11
	v_cvt_pk_bf16_f32 v41, v44, v41
	v_mul_f32_e32 v3, v3, v40
	ds_write2_b32 v35, v33, v41 offset1:1
	v_mul_f32_e32 v33, v67, v40
	v_fma_f32 v3, v18, v3, v19
	v_mul_f32_e32 v2, v2, v40
	v_fma_f32 v33, v12, v33, v13
	v_cvt_pk_bf16_f32 v3, v62, v3
	v_fma_f32 v2, v20, v2, v21
	v_cvt_pk_bf16_f32 v33, v45, v33
	ds_write2_b32 v32, v7, v3 offset1:1
	v_cvt_pk_bf16_f32 v2, v63, v2
	v_cvt_pk_bf16_f32 v3, v6, v57
	ds_write2_b32 v37, v34, v33 offset1:1
	v_mul_f32_e32 v33, v68, v40
	ds_write2_b32 v47, v3, v2 offset1:1
	v_mul_f32_e32 v2, v5, v40
	v_fma_f32 v33, v14, v33, v15
	v_fma_f32 v2, v22, v2, v23
	v_cvt_pk_bf16_f32 v33, v60, v33
	v_cvt_pk_bf16_f32 v34, v36, v54
	v_cvt_pk_bf16_f32 v2, v64, v2
	v_cvt_pk_bf16_f32 v3, v48, v58
	ds_write2_b32 v39, v34, v33 offset1:1
	v_mul_f32_e32 v33, v69, v40
	ds_write2_b32 v49, v3, v2 offset1:1
	v_mul_f32_e32 v2, v4, v40
	v_fma_f32 v33, v16, v33, v17
	v_fma_f32 v2, v24, v2, v25
	v_cvt_pk_bf16_f32 v33, v61, v33
	v_cvt_pk_bf16_f32 v34, v38, v55
	v_cvt_pk_bf16_f32 v2, v65, v2
	v_cvt_pk_bf16_f32 v3, v50, v59
	v_add_u32_e32 v32, 8, v32
	ds_write2_b32 v46, v34, v33 offset1:1
	ds_write2_b32 v51, v3, v2 offset1:1
	s_cbranch_scc0 .LBB0_519
	v_readlane_b32 s12, v251, 13
	s_lshl_b32 s0, s9, 5
	v_and_b32_e32 v0, 48, v8
	v_mov_b32_e32 v1, v161
	v_readlane_b32 s13, v251, 14
	s_and_b32 s11, s0, 0xffffff80
	s_and_b32 s0, s10, 0xffffffc0
	v_lshl_add_u64 v[64:65], s[12:13], 0, v[0:1]
	s_lshl_b32 s12, s4, 7
	s_lshl_b32 s1, s5, 1
	v_readlane_b32 s14, v250, 11
	v_readlane_b32 s15, v250, 12
	s_add_u32 s13, s14, s1
	s_addc_u32 s16, s15, 0
	s_ashr_i32 s1, s0, 31
	s_lshl_b64 s[14:15], s[0:1], 1
	s_add_u32 s14, s13, s14
	v_lshrrev_b32_e32 v2, 4, v8
	s_addc_u32 s15, s16, s15
	s_add_i32 s0, s0, s5
	v_and_b32_e32 v81, 15, v9
	v_lshl_or_b32 v0, v2, 2, s0
	s_lshl_b32 s0, s4, 14
	v_lshlrev_b32_e32 v160, 3, v2
	v_lshl_or_b32 v2, v81, 7, s0
	v_readlane_b32 s0, v250, 13
	v_ashrrev_i32_e32 v1, 31, v0
	v_readlane_b32 s1, v250, 14
	v_and_b32_e32 v3, 48, v9
	v_lshl_add_u64 v[66:67], s[14:15], 0, v[160:161]
	v_lshl_add_u64 v[68:69], v[0:1], 1, s[0:1]
	s_lshr_b32 s0, s10, 6
	s_mulk_i32 s0, 0x4100
	v_mov_b32_e32 v0, s0
	s_movk_i32 s0, 0x104
	v_mad_u32_u24 v0, v81, s0, v0
	v_or_b32_e32 v89, s11, v81
	s_or_b32 s13, s11, 16
	s_or_b32 s14, s11, 32
	s_or_b32 s15, s11, 48
	v_add3_u32 v103, v0, v3, 0
	s_mov_b64 s[4:5], -1
	v_lshlrev_b32_e32 v108, 1, v2
	s_mov_b32 s10, 0
	s_waitcnt lgkmcnt(0)
	s_barrier
